# v27 with the final RMSNorm phase's four row loads issued together (one round trip per row instead of four)
# speedup vs baseline: 1.0039x; 1.0039x over previous
.LBB0_169:
	global_load_dwordx2 v[44:45], v[34:35], off
	global_load_dwordx4 v[40:43], v[36:37], off offset:-2048
	global_load_dwordx4 v[56:59], v[36:37], off offset:-1024
	global_load_dwordx4 v[60:63], v[36:37], off
	global_load_dwordx4 v[64:67], v[36:37], off offset:1024
	s_movk_i32 s0, 0xf000
	v_add_co_u32_e32 v48, vcc, s0, v32
	v_add_u32_e32 v38, s8, v38
	s_nop 0
	v_addc_co_u32_e32 v49, vcc, -1, v33, vcc
	v_lshl_add_u64 v[34:35], v[34:35], 0, s[20:21]
	s_waitcnt vmcnt(4)
	v_ffbh_u32_e32 v39, v45
	v_min_u32_e32 v39, 32, v39
	v_lshlrev_b64 v[44:45], v39, v[44:45]
	v_min_u32_e32 v44, 1, v44
	v_or_b32_e32 v44, v45, v44
	v_cvt_f32_u32_e32 v44, v44
	v_sub_u32_e32 v39, 32, v39
	s_waitcnt vmcnt(3)
	v_lshlrev_b32_e32 v46, 16, v40
	v_and_b32_e32 v47, 0xffff0000, v40
	v_ldexp_f32 v39, v44, v39
	v_fmamk_f32 v39, v39, 0x30000000, v158
	v_mul_f32_e32 v44, 0x4b800000, v39
	v_cmp_gt_f32_e32 vcc, s37, v39
	v_lshlrev_b32_e32 v40, 16, v41
	v_and_b32_e32 v41, 0xffff0000, v41
	v_cndmask_b32_e32 v39, v39, v44, vcc
	v_rsq_f32_e32 v39, v39
	v_lshlrev_b32_e32 v50, 16, v42
	v_and_b32_e32 v51, 0xffff0000, v42
	v_lshlrev_b32_e32 v42, 16, v43
	v_mul_f32_e32 v44, 0x45800000, v39
	v_cndmask_b32_e32 v52, v39, v44, vcc
	v_and_b32_e32 v43, 0xffff0000, v43
	v_pk_mul_f32 v[44:45], v[52:53], v[46:47] op_sel_hi:[0,1]
	v_pk_mul_f32 v[46:47], v[52:53], v[40:41] op_sel_hi:[0,1]
	v_pk_mul_f32 v[40:41], v[52:53], v[50:51] op_sel_hi:[0,1]
	v_pk_mul_f32 v[42:43], v[52:53], v[42:43] op_sel_hi:[0,1]
	v_pk_mul_f32 v[46:47], v[30:31], v[46:47]
	v_pk_mul_f32 v[44:45], v[28:29], v[44:45]
	v_pk_mul_f32 v[42:43], v[26:27], v[42:43]
	v_pk_mul_f32 v[40:41], v[24:25], v[40:41]
	global_store_dwordx4 v[48:49], v[44:47], off offset:-2064
	global_store_dwordx4 v[48:49], v[40:43], off offset:-2048
	v_cmp_lt_i32_e32 vcc, s9, v38
	s_or_b64 s[14:15], vcc, s[14:15]
	s_waitcnt vmcnt(4)
	v_lshlrev_b32_e32 v44, 16, v56
	v_and_b32_e32 v45, 0xffff0000, v56
	v_lshlrev_b32_e32 v40, 16, v57
	v_and_b32_e32 v41, 0xffff0000, v57
	v_lshlrev_b32_e32 v46, 16, v58
	v_and_b32_e32 v47, 0xffff0000, v58
	v_lshlrev_b32_e32 v42, 16, v59
	v_and_b32_e32 v43, 0xffff0000, v59
	v_pk_mul_f32 v[44:45], v[52:53], v[44:45] op_sel_hi:[0,1]
	v_pk_mul_f32 v[50:51], v[52:53], v[40:41] op_sel_hi:[0,1]
	v_pk_mul_f32 v[40:41], v[52:53], v[46:47] op_sel_hi:[0,1]
	v_pk_mul_f32 v[42:43], v[52:53], v[42:43] op_sel_hi:[0,1]
	v_pk_mul_f32 v[46:47], v[22:23], v[50:51]
	v_pk_mul_f32 v[44:45], v[20:21], v[44:45]
	v_pk_mul_f32 v[42:43], v[18:19], v[42:43]
	v_pk_mul_f32 v[40:41], v[16:17], v[40:41]
	global_store_dwordx4 v[48:49], v[44:47], off offset:-16
	global_store_dwordx4 v[32:33], v[40:43], off offset:-4096
	s_waitcnt vmcnt(5)
	v_lshlrev_b32_e32 v44, 16, v60
	v_and_b32_e32 v45, 0xffff0000, v60
	v_lshlrev_b32_e32 v40, 16, v61
	v_and_b32_e32 v41, 0xffff0000, v61
	v_lshlrev_b32_e32 v46, 16, v62
	v_and_b32_e32 v47, 0xffff0000, v62
	v_lshlrev_b32_e32 v42, 16, v63
	v_and_b32_e32 v43, 0xffff0000, v63
	v_pk_mul_f32 v[44:45], v[52:53], v[44:45] op_sel_hi:[0,1]
	v_pk_mul_f32 v[48:49], v[52:53], v[40:41] op_sel_hi:[0,1]
	v_pk_mul_f32 v[40:41], v[52:53], v[46:47] op_sel_hi:[0,1]
	v_pk_mul_f32 v[42:43], v[52:53], v[42:43] op_sel_hi:[0,1]
	v_pk_mul_f32 v[46:47], v[6:7], v[48:49]
	v_pk_mul_f32 v[44:45], v[4:5], v[44:45]
	v_pk_mul_f32 v[42:43], v[14:15], v[42:43]
	v_pk_mul_f32 v[40:41], v[12:13], v[40:41]
	global_store_dwordx4 v[32:33], v[44:47], off offset:-2064
	global_store_dwordx4 v[32:33], v[40:43], off offset:-2048
	v_lshl_add_u64 v[36:37], v[36:37], 0, s[22:23]
	s_waitcnt vmcnt(6)
	v_lshlrev_b32_e32 v44, 16, v64
	v_and_b32_e32 v45, 0xffff0000, v64
	v_lshlrev_b32_e32 v40, 16, v65
	v_and_b32_e32 v41, 0xffff0000, v65
	v_lshlrev_b32_e32 v46, 16, v66
	v_and_b32_e32 v47, 0xffff0000, v66
	v_lshlrev_b32_e32 v42, 16, v67
	v_and_b32_e32 v43, 0xffff0000, v67
	v_pk_mul_f32 v[44:45], v[52:53], v[44:45] op_sel_hi:[0,1]
	v_pk_mul_f32 v[48:49], v[52:53], v[40:41] op_sel_hi:[0,1]
	v_pk_mul_f32 v[40:41], v[52:53], v[46:47] op_sel_hi:[0,1]
	v_pk_mul_f32 v[42:43], v[52:53], v[42:43] op_sel_hi:[0,1]
	v_pk_mul_f32 v[46:47], v[10:11], v[48:49]
	v_pk_mul_f32 v[44:45], v[8:9], v[44:45]
	v_pk_mul_f32 v[42:43], v[2:3], v[42:43]
	v_pk_mul_f32 v[40:41], v[0:1], v[40:41]
	global_store_dwordx4 v[32:33], v[44:47], off offset:-16
	global_store_dwordx4 v[32:33], v[40:43], off
	v_lshl_add_u64 v[32:33], v[32:33], 0, s[18:19]
	s_andn2_b64 exec, exec, s[14:15]
	s_cbranch_execnz .LBB0_169
